# P4: one-time half-chunk stagger (s_sleep 25) of waves 4-7 at phase start, on top of best
# speedup vs baseline: 1.0155x; 1.0064x over previous
; __device__ __forceinline__ void p4_attn(const Params& p, unsigned char* lds, int bid, int nb, bool dry) {
;   LAS unsigned char* cbuf = (LAS unsigned char*)lds;
;   LAS float* biasd = (LAS float*)((LAS unsigned char*)lds + 2 * CBUF);
;   LAS unsigned short* idxs = (LAS unsigned short*)((LAS unsigned char*)lds + 2 * CBUF + 129 * 32 * 4);
;   const bf16_t* ckvn = (const bf16_t*)(p.ws + OFF_CKVN); const unsigned short* idxg = (const unsigned short*)(p.ws + OFF_IDX);
;   unsigned char* QL = p.ws + OFF_QL0;
;   int tid = threadIdx.x; asm volatile("" : "+v"(tid));
;   const int lane = tid & 63, wid = __builtin_amdgcn_readfirstlane(tid >> 6), g = lane >> 4, r16 = lane & 15;
;   for (int i = tid; i < 129 * 32; i += 512) {
;     const int d = i >> 5, hd = i & 31; int bucket = d;
;     if (d >= 16) { bucket = 16 + (d >= 19) + (d >= 21) + (d >= 24) + (d >= 27) + (d >= 31) + (d >= 35) + (d >= 40) + (d >= 46) + (d >= 52) + (d >= 59) + (d >= 67) + (d >= 77) + (d >= 87) + (d >= 99) + (d >= 113); }
;     biasd[i] = ((const float*)(p.ws + OFF_SMALL))[SM_RELB + bucket * 32 + hd] * LOG2E;
;   }
;   LAS unsigned* pcnt = (LAS unsigned*)((LAS unsigned char*)lds + 2 * CBUF + 129 * 32 * 4 + 2048) + (wid >> 1);
;   if (tid < 4) ((LAS unsigned*)((LAS unsigned char*)lds + 2 * CBUF + 129 * 32 * 4 + 2048))[tid] = 0u;
;   __syncthreads();
;   unsigned epoch = 0u;
;   const int tok = wid >> 1, hw = wid & 1, head = hw * 16 + r16;
;   const float SC = 0.08838834764831845f * LOG2E;
;   const int qoff = 16 * (g ^ (r16 >> 3));
;   const int q4 = r16 >> 2, pp = r16 & 3;
;   const int troff = (4 * g + q4) * CROW + 16 * ((pp >> 1) ^ (g >> 1)) + 8 * (pp & 1);
;   const int wrow = 16 * hw + 8 * (lane >> 5), wch = lane & 31;
;   for (int round = 0; round * nb < T / 4; ++round) {
;     const int item = round * nb + (bid + round * 37) % nb;
;     const int tg0 = item * 4, b = tg0 >> 11, t0 = tg0 & 2047, t = t0 + tok, tg = tg0 + tok;
;     const int nk = min(t + 1, 256), nkmax = min(t0 + 4, 256), nch = (nkmax + 31) >> 5;
;     ((LAS unsigned*)idxs)[tid] = ((const unsigned*)(idxg + (size_t)tg0 * 256))[tid];
;     unsigned char* qrow = QL + (size_t)tg * 8192 + head * 256;
;     bf16x8 qB[8];
; #pragma unroll
;     for (int s = 0; s < 8; ++s) { const u32x2 qw = *(const u32x2*)(qrow + 32 * s + 8 * g);
;       typedef float f32x2v __attribute__((ext_vector_type(2)));
.LBB0_988:
	s_or_b64 exec, exec, s[4:5]
	v_cmp_gt_i32_e32 vcc, 4, v2
	s_and_saveexec_b64 s[4:5], vcc
	v_add_u32_e32 v0, 0x26880, v0
	v_mov_b32_e32 v1, 0
	ds_write_b32 v0, v1
	s_or_b64 exec, exec, s[4:5]
	v_bfe_u32 v5, v2, 4, 2
	v_bfe_u32 v0, v2, 3, 1
	v_mov_b32_e32 v0, v5
	v_lshlrev_b32_e32 v162, 4, v0
	v_bfe_u32 v0, v2, 2, 2
	v_lshlrev_b32_e32 v148, 2, v5
	v_or_b32_e32 v0, v148, v0
	s_ashr_i32 s0, s3, 7
	s_lshr_b32 s3, s3, 2
	v_mul_u32_u24_e32 v163, 0x220, v0
	v_lshrrev_b32_e32 v0, 1, v2
	v_bfe_u32 v8, v2, 5, 1
	v_and_b32_e32 v6, 15, v2
	s_and_b32 s3, s3, 16
	v_and_b32_e32 v0, 1, v0
	v_readlane_b32 s4, v254, 36
	v_or_b32_e32 v7, s3, v6
	v_lshlrev_b32_e32 v164, 4, v0
	v_lshlrev_b32_e32 v0, 3, v2
	v_ashrrev_i32_e32 v3, 31, v2
	v_readlane_b32 s5, v254, 37
	v_and_b32_e32 v165, 8, v0
	v_and_b32_e32 v10, 31, v2
	v_lshl_add_u64 v[150:151], v[2:3], 2, s[4:5]
	v_lshlrev_b32_e32 v0, 8, v7
	v_mov_b32_e32 v1, 0
	v_readlane_b32 s4, v254, 42
	v_lshl_add_u64 v[152:153], s[92:93], 0, v[0:1]
	v_lshlrev_b32_e32 v0, 4, v10
	v_readlane_b32 s5, v254, 43
	v_lshl_or_b32 v9, v8, 3, s3
	s_add_i32 s3, 0, 0x26080
	v_lshl_add_u64 v[156:157], s[4:5], 0, v[0:1]
	s_lshl_b32 s4, s0, 9
	s_lshl_b32 s2, s0, 2
	v_lshl_add_u32 v166, v2, 2, s3
	s_add_i32 s3, s3, s4
	s_mul_i32 s4, s0, 0x4400
	v_and_b32_e32 v0, 31, v2
	s_add_i32 s2, s2, 0
	v_and_b32_e32 v4, 63, v2
	s_add_i32 s5, s4, 0
	v_lshlrev_b32_e32 v0, 4, v0
	s_add_i32 s4, 0, 0x22000
	v_mul_u32_u24_e32 v2, 0x220, v9
	s_mov_b32 s1, 0
	s_add_i32 s2, s2, 0x26880
	v_lshlrev_b32_e32 v154, 3, v5
	v_mov_b32_e32 v155, v1
	v_cmp_eq_u32_e64 s[8:9], 0, v4
	v_lshl_add_u32 v167, v9, 1, s3
	v_mul_u32_u24_e32 v168, 0x220, v6
	v_lshl_add_u32 v169, v7, 2, s4
	v_mov_b32_e32 v149, v1
	v_add3_u32 v170, s5, v0, v2
	s_movk_i32 s16, 0x80
	s_mov_b32 s4, 0x3e0293ee
	s_mov_b32 s17, 0xf149f2ca
	s_mov_b32 s18, 0x41800000
	v_mov_b32_e32 v171, 9
	v_mov_b32_e32 v172, 0x80
	v_mov_b32_e32 v173, 0xf149f2ca
	s_mov_b32 s10, 0
	s_mov_b32 s19, 0
	s_mov_b32 s20, 0
	s_lshl_b32 s28, s88, 11
	s_mov_b32 s29, 0
	v_lshl_add_u64 v[2:3], v[150:151], 0, s[28:29]
	global_load_dword v255, v[2:3], off
	s_lshl_b32 s28, s88, 2
	s_add_i32 s28, s28, s0
	s_lshl_b32 s28, s28, 13
	v_lshl_add_u64 v[194:195], v[152:153], 0, s[28:29]
	v_lshl_add_u64 v[194:195], v[194:195], 0, v[154:155]
	global_load_dwordx2 v[218:219], v[194:195], off
	global_load_dwordx2 v[220:221], v[194:195], off offset:32
	global_load_dwordx2 v[222:223], v[194:195], off offset:64
	global_load_dwordx2 v[224:225], v[194:195], off offset:96
	global_load_dwordx2 v[226:227], v[194:195], off offset:128
	global_load_dwordx2 v[228:229], v[194:195], off offset:160
	global_load_dwordx2 v[230:231], v[194:195], off offset:192
	global_load_dwordx2 v[232:233], v[194:195], off offset:224
	s_waitcnt vmcnt(0)
	s_waitcnt lgkmcnt(0)
	s_barrier
	s_cmp_lt_u32 s0, 2
	s_cbranch_scc1 .Lp4_nostagger
	s_sleep 25
.Lp4_nostagger:
.LBB0_991:
	s_mul_i32 s11, s20, 37
	s_add_i32 s11, s11, s88
	s_ashr_i32 s12, s11, 31
	s_abs_i32 s11, s11
	v_readlane_b32 s13, v254, 32
	s_mul_hi_u32 s13, s11, s13
	v_readlane_b32 s14, v254, 33
	s_mul_i32 s13, s13, s14
	s_sub_i32 s11, s11, s13
	s_sub_i32 s13, s11, s14
	s_cmp_ge_u32 s11, s14
	s_cselect_b32 s11, s13, s11
	s_sub_i32 s13, s11, s14
	s_cmp_ge_u32 s11, s14
	s_cselect_b32 s11, s13, s11
	s_xor_b32 s11, s11, s12
	s_sub_i32 s22, s11, s12
	s_add_i32 s21, s22, s10
	s_lshl_b32 s10, s21, 2
	s_add_i32 s12, s10, s0
	s_ashr_i32 s11, s10, 31
	s_ashr_i32 s13, s12, 31
	s_lshl_b64 s[14:15], s[10:11], 9
	s_lshl_b64 s[12:13], s[12:13], 13
	v_lshl_add_u64 v[158:159], v[152:153], 0, s[12:13]
	s_waitcnt vmcnt(12)
	ds_write_b32 v166, v255
	s_and_saveexec_b64 s[12:13], s[8:9]
	s_cbranch_execz .LBB0_994
	s_mov_b64 s[14:15], exec
	v_mbcnt_lo_u32_b32 v0, s14, 0
	v_mbcnt_hi_u32_b32 v0, s15, v0
	v_cmp_eq_u32_e32 vcc, 0, v0
	s_and_b64 s[24:25], exec, vcc
	s_mov_b64 exec, s[24:25]
	s_bcnt1_i32_b64 s11, s[14:15]
	v_mov_b32_e32 v0, s2
	v_mov_b32_e32 v2, s11
	ds_add_u32 v0, v2
